# ST4b: same stagger with the odd XCD-local index workgroups delayed instead
# baseline (speedup 1.0000x reference)
.Lfbq_out:
.LBB0_992:
	s_or_b64 exec, exec, s[0:1]
	v_readlane_b32 s4, v232, 14
	s_nop 3
	s_bitcmp1_b32 s4, 5
	s_cbranch_scc0 .Lst_go
	s_memrealtime s[4:5]
	s_waitcnt lgkmcnt(0)
	s_add_u32 s4, s4, 800
	s_addc_u32 s5, s5, 0
